# v6 + attention: exp/sum/pack of P fragment k+1 interleaved between the PV MFMAs of fragment k (only fragment 0 is produced before the first PV MFMA)
# speedup vs baseline: 1.0066x; 1.0024x over previous
.LBB0_1410:
	s_lshl_b32 s0, s70, 14
	s_add_i32 s0, s0, 0
	s_add_i32 s0, s0, 0x12000
	v_add_u32_e32 v16, s0, v163
	ds_read_b64_tr_b16 v[226:227], v16 offset:0
	ds_read_b64_tr_b16 v[228:229], v16 offset:2048
	v_add_u32_e32 v17, s0, v212
	ds_read_b64_tr_b16 v[230:231], v17 offset:0
	ds_read_b64_tr_b16 v[232:233], v17 offset:2048
	ds_read_b64_tr_b16 v[234:235], v16 offset:1024
	ds_read_b64_tr_b16 v[236:237], v16 offset:3072
	v_exp_f32_e32 v34, v34
	v_exp_f32_e32 v35, v35
	v_add_f32_e32 v220, v220, v34
	v_add_f32_e32 v220, v220, v35
	v_exp_f32_e32 v36, v36
	v_exp_f32_e32 v37, v37
	v_add_f32_e32 v220, v220, v36
	v_add_f32_e32 v220, v220, v37
	v_exp_f32_e32 v38, v38
	v_exp_f32_e32 v39, v39
	v_add_f32_e32 v220, v220, v38
	v_add_f32_e32 v220, v220, v39
	v_exp_f32_e32 v40, v40
	v_exp_f32_e32 v41, v41
	v_add_f32_e32 v220, v220, v40
	v_add_f32_e32 v220, v220, v41
	v_cvt_pk_bf16_f32 v4, v34, v35
	v_cvt_pk_bf16_f32 v5, v36, v37
	v_cvt_pk_bf16_f32 v6, v38, v39
	v_cvt_pk_bf16_f32 v7, v40, v41
	s_nop 1
	s_setprio 1
	ds_read_b64_tr_b16 v[238:239], v17 offset:1024
	ds_read_b64_tr_b16 v[240:241], v17 offset:3072
	s_waitcnt lgkmcnt(6)
	v_mfma_f32_32x32x16_bf16 v[98:113], v[226:229], v[4:7], v[98:113]
	ds_read_b64_tr_b16 v[226:227], v16 offset:4096
	ds_read_b64_tr_b16 v[228:229], v16 offset:6144
	v_exp_f32_e32 v42, v42
	v_exp_f32_e32 v43, v43
	v_add_f32_e32 v220, v220, v42
	v_add_f32_e32 v220, v220, v43
	s_waitcnt lgkmcnt(6)
	v_mfma_f32_32x32x16_bf16 v[82:97], v[230:233], v[4:7], v[82:97]
	ds_read_b64_tr_b16 v[230:231], v17 offset:4096
	ds_read_b64_tr_b16 v[232:233], v17 offset:6144
	v_exp_f32_e32 v44, v44
	v_exp_f32_e32 v45, v45
	v_add_f32_e32 v220, v220, v44
	v_add_f32_e32 v220, v220, v45
	s_waitcnt lgkmcnt(6)
	v_mfma_f32_32x32x16_bf16 v[66:81], v[234:237], v[4:7], v[66:81]
	ds_read_b64_tr_b16 v[234:235], v16 offset:5120
	ds_read_b64_tr_b16 v[236:237], v16 offset:7168
	v_exp_f32_e32 v46, v46
	v_exp_f32_e32 v47, v47
	v_add_f32_e32 v220, v220, v46
	v_add_f32_e32 v220, v220, v47
	s_waitcnt lgkmcnt(6)
	v_mfma_f32_32x32x16_bf16 v[50:65], v[238:241], v[4:7], v[50:65]
	ds_read_b64_tr_b16 v[4:5], v17 offset:5120
	ds_read_b64_tr_b16 v[6:7], v17 offset:7168
	v_exp_f32_e32 v48, v48
	v_exp_f32_e32 v49, v49
	v_add_f32_e32 v220, v220, v48
	v_add_f32_e32 v220, v220, v49
	v_cvt_pk_bf16_f32 v8, v42, v43
	v_cvt_pk_bf16_f32 v9, v44, v45
	v_cvt_pk_bf16_f32 v10, v46, v47
	v_cvt_pk_bf16_f32 v11, v48, v49
	s_nop 1
	s_waitcnt lgkmcnt(6)
	v_mfma_f32_32x32x16_bf16 v[98:113], v[226:229], v[8:11], v[98:113]
	ds_read_b64_tr_b16 v[226:227], v16 offset:8192
	ds_read_b64_tr_b16 v[228:229], v16 offset:10240
	v_exp_f32_e32 v18, v18
	v_exp_f32_e32 v19, v19
	v_add_f32_e32 v220, v220, v18
	v_add_f32_e32 v220, v220, v19
	s_waitcnt lgkmcnt(6)
	v_mfma_f32_32x32x16_bf16 v[82:97], v[230:233], v[8:11], v[82:97]
	ds_read_b64_tr_b16 v[230:231], v17 offset:8192
	ds_read_b64_tr_b16 v[232:233], v17 offset:10240
	v_exp_f32_e32 v20, v20
	v_exp_f32_e32 v21, v21
	v_add_f32_e32 v220, v220, v20
	v_add_f32_e32 v220, v220, v21
	s_waitcnt lgkmcnt(6)
	v_mfma_f32_32x32x16_bf16 v[66:81], v[234:237], v[8:11], v[66:81]
	ds_read_b64_tr_b16 v[234:235], v16 offset:9216
	ds_read_b64_tr_b16 v[236:237], v16 offset:11264
	v_exp_f32_e32 v22, v22
	v_exp_f32_e32 v23, v23
	v_add_f32_e32 v220, v220, v22
	v_add_f32_e32 v220, v220, v23
	s_waitcnt lgkmcnt(6)
	v_mfma_f32_32x32x16_bf16 v[50:65], v[4:7], v[8:11], v[50:65]
	ds_read_b64_tr_b16 v[4:5], v17 offset:9216
	ds_read_b64_tr_b16 v[6:7], v17 offset:11264
	v_exp_f32_e32 v24, v24
	v_exp_f32_e32 v25, v25
	v_add_f32_e32 v220, v220, v24
	v_add_f32_e32 v220, v220, v25
	v_cvt_pk_bf16_f32 v12, v18, v19
	v_cvt_pk_bf16_f32 v13, v20, v21
	v_cvt_pk_bf16_f32 v14, v22, v23
	v_cvt_pk_bf16_f32 v15, v24, v25
	s_nop 1
	s_waitcnt lgkmcnt(6)
	v_mfma_f32_32x32x16_bf16 v[98:113], v[226:229], v[12:15], v[98:113]
	ds_read_b64_tr_b16 v[8:9], v16 offset:12288
	ds_read_b64_tr_b16 v[10:11], v16 offset:14336
	v_exp_f32_e32 v26, v26
	v_exp_f32_e32 v27, v27
	v_add_f32_e32 v220, v220, v26
	v_add_f32_e32 v220, v220, v27
	s_waitcnt lgkmcnt(6)
	v_mfma_f32_32x32x16_bf16 v[82:97], v[230:233], v[12:15], v[82:97]
	ds_read_b64_tr_b16 v[226:227], v17 offset:12288
	ds_read_b64_tr_b16 v[228:229], v17 offset:14336
	v_exp_f32_e32 v28, v28
	v_exp_f32_e32 v29, v29
	v_add_f32_e32 v220, v220, v28
	v_add_f32_e32 v220, v220, v29
	s_waitcnt lgkmcnt(6)
	v_mfma_f32_32x32x16_bf16 v[66:81], v[234:237], v[12:15], v[66:81]
	ds_read_b64_tr_b16 v[230:231], v16 offset:13312
	ds_read_b64_tr_b16 v[232:233], v16 offset:15360
	v_exp_f32_e32 v30, v30
	v_exp_f32_e32 v31, v31
	v_add_f32_e32 v220, v220, v30
	v_add_f32_e32 v220, v220, v31
	s_waitcnt lgkmcnt(6)
	v_mfma_f32_32x32x16_bf16 v[50:65], v[4:7], v[12:15], v[50:65]
	ds_read_b64_tr_b16 v[4:5], v17 offset:13312
	ds_read_b64_tr_b16 v[6:7], v17 offset:15360
	v_exp_f32_e32 v32, v32
	v_exp_f32_e32 v33, v33
	v_add_f32_e32 v220, v220, v32
	v_add_f32_e32 v220, v220, v33
	v_cvt_pk_bf16_f32 v222, v26, v27
	v_cvt_pk_bf16_f32 v223, v28, v29
	v_cvt_pk_bf16_f32 v224, v30, v31
	v_cvt_pk_bf16_f32 v225, v32, v33
	s_nop 1
	s_waitcnt lgkmcnt(6)
	v_mfma_f32_32x32x16_bf16 v[98:113], v[8:11], v[222:225], v[98:113]
	s_waitcnt lgkmcnt(4)
	v_mfma_f32_32x32x16_bf16 v[82:97], v[226:229], v[222:225], v[82:97]
	s_waitcnt lgkmcnt(2)
	v_mfma_f32_32x32x16_bf16 v[66:81], v[230:233], v[222:225], v[66:81]
	s_waitcnt lgkmcnt(0)
	v_mfma_f32_32x32x16_bf16 v[50:65], v[4:7], v[222:225], v[50:65]
	s_setprio 0
